# obuf_v80 + w_out^T k-blocked ([kt][n][32]) for the phase-5 B operand (main and sample-row GEMM), written that way by phase 0
# speedup vs baseline: 1.0278x; 1.0278x over previous
.Ltr_loop:
	s_sub_i32 s80, s74, 0x2040
	s_movk_i32 s86, 0x400
	s_mov_b32 s92, 0x10a40000
	s_cmpk_lt_u32 s80, 0x420
	s_cselect_b32 s84, s64, s46
	s_cselect_b32 s85, s65, s47
	s_cselect_b32 s86, 0x1010, s86
	s_cselect_b32 s92, 0x10200000, s92
	s_cselect_b64 s[88:89], -1, 0
	s_mov_b32 s96, 6
	s_mov_b32 s97, 0x10000
	s_cselect_b32 s97, 0x42000, s97
	s_mov_b32 s98, 0x20000
	s_cselect_b32 s98, 0x84000, s98
	s_cselect_b32 s81, 0, 0x420
	s_sub_u32 s80, s80, s81
	s_lshr_b32 s82, s80, 4
	s_and_b32 s83, s80, 15
	s_lshl_b32 s87, s86, 4
	s_add_u32 s92, s20, s92
	s_addc_u32 s93, s21, 0
	v_lshl_add_u32 v66, s82, 6, v64
	v_add_u32_e32 v67, 16, v66
	v_add_u32_e32 v68, 0xfffff800, v66
	v_cmp_gt_u32_e32 vcc, 0x800, v66
	s_nop 1
	v_cndmask_b32_e32 v69, v67, v66, vcc
	v_cmp_gt_u32_e32 vcc, 0x1000, v66
	s_nop 1
	v_cndmask_b32_e32 v69, v68, v69, vcc
	v_cmp_gt_u32_e64 s[90:91], s86, v66
	v_cndmask_b32_e64 v69, v66, v69, s[88:89]
	s_orn2_b64 s[90:91], s[90:91], s[88:89]
	v_lshl_add_u32 v70, s83, 6, v65
	v_mul_lo_u32 v70, v70, s86
	v_add_lshl_u32 v70, v70, v69, 2
	v_mov_b32_e32 v72, 0
	v_mov_b32_e32 v73, 0
	v_mov_b32_e32 v74, 0
	v_mov_b32_e32 v75, 0
	v_mov_b32_e32 v76, 0
	v_mov_b32_e32 v77, 0
	v_mov_b32_e32 v78, 0
	v_mov_b32_e32 v79, 0
	v_mov_b32_e32 v80, 0
	v_mov_b32_e32 v81, 0
	v_mov_b32_e32 v82, 0
	v_mov_b32_e32 v83, 0
	v_mov_b32_e32 v84, 0
	v_mov_b32_e32 v85, 0
	v_mov_b32_e32 v86, 0
	v_mov_b32_e32 v87, 0
	s_mov_b64 vcc, exec
	s_and_b64 exec, exec, s[90:91]
	global_load_dword v72, v70, s[84:85] nt
	v_add_u32_e32 v70, s87, v70
	global_load_dword v73, v70, s[84:85] nt
	v_add_u32_e32 v70, s87, v70
	global_load_dword v74, v70, s[84:85] nt
	v_add_u32_e32 v70, s87, v70
	global_load_dword v75, v70, s[84:85] nt
	v_add_u32_e32 v70, s87, v70
	global_load_dword v76, v70, s[84:85] nt
	v_add_u32_e32 v70, s87, v70
	global_load_dword v77, v70, s[84:85] nt
	v_add_u32_e32 v70, s87, v70
	global_load_dword v78, v70, s[84:85] nt
	v_add_u32_e32 v70, s87, v70
	global_load_dword v79, v70, s[84:85] nt
	v_add_u32_e32 v70, s87, v70
	global_load_dword v80, v70, s[84:85] nt
	v_add_u32_e32 v70, s87, v70
	global_load_dword v81, v70, s[84:85] nt
	v_add_u32_e32 v70, s87, v70
	global_load_dword v82, v70, s[84:85] nt
	v_add_u32_e32 v70, s87, v70
	global_load_dword v83, v70, s[84:85] nt
	v_add_u32_e32 v70, s87, v70
	global_load_dword v84, v70, s[84:85] nt
	v_add_u32_e32 v70, s87, v70
	global_load_dword v85, v70, s[84:85] nt
	v_add_u32_e32 v70, s87, v70
	global_load_dword v86, v70, s[84:85] nt
	v_add_u32_e32 v70, s87, v70
	global_load_dword v87, v70, s[84:85] nt
	s_mov_b64 exec, vcc
	s_barrier
	s_waitcnt vmcnt(0)
	ds_write_b32 v71, v72
	ds_write_b32 v71, v73 offset:1040
	ds_write_b32 v71, v74 offset:2080
	ds_write_b32 v71, v75 offset:3120
	ds_write_b32 v71, v76 offset:4160
	ds_write_b32 v71, v77 offset:5200
	ds_write_b32 v71, v78 offset:6240
	ds_write_b32 v71, v79 offset:7280
	ds_write_b32 v71, v80 offset:8320
	ds_write_b32 v71, v81 offset:9360
	ds_write_b32 v71, v82 offset:10400
	ds_write_b32 v71, v83 offset:11440
	ds_write_b32 v71, v84 offset:12480
	ds_write_b32 v71, v85 offset:13520
	ds_write_b32 v71, v86 offset:14560
	ds_write_b32 v71, v87 offset:15600
	s_waitcnt lgkmcnt(0)
	s_barrier
	ds_read_b32 v72, v90
	ds_read_b32 v73, v90 offset:260
	ds_read_b32 v74, v90 offset:520
	ds_read_b32 v75, v90 offset:780
	ds_read_b32 v76, v90 offset:1040
	ds_read_b32 v77, v90 offset:1300
	ds_read_b32 v78, v90 offset:1560
	ds_read_b32 v79, v90 offset:1820
	ds_read_b32 v80, v90 offset:8320
	ds_read_b32 v81, v90 offset:8580
	ds_read_b32 v82, v90 offset:8840
	ds_read_b32 v83, v90 offset:9100
	ds_read_b32 v84, v90 offset:9360
	ds_read_b32 v85, v90 offset:9620
	ds_read_b32 v86, v90 offset:9880
	ds_read_b32 v87, v90 offset:10140
	v_lshl_add_u32 v91, s82, 6, v88
	v_lshlrev_b32_e32 v91, s96, v91
	v_lshl_add_u32 v91, v89, 4, v91
	s_mul_i32 s81, s83, s98
	v_add_u32_e32 v91, s81, v91
	v_add_u32_e32 v100, s97, v91
	s_waitcnt lgkmcnt(0)
	v_cvt_pk_bf16_f32 v92, v72, v73
	v_cvt_pk_bf16_f32 v93, v74, v75
	v_cvt_pk_bf16_f32 v94, v76, v77
	v_cvt_pk_bf16_f32 v95, v78, v79
	v_cvt_pk_bf16_f32 v96, v80, v81
	v_cvt_pk_bf16_f32 v97, v82, v83
	v_cvt_pk_bf16_f32 v98, v84, v85
	v_cvt_pk_bf16_f32 v99, v86, v87
	global_store_dwordx4 v91, v[92:95], s[92:93]
	global_store_dwordx4 v100, v[96:99], s[92:93]
	s_add_i32 s74, s74, s22
	s_cmpk_lt_i32 s74, 0x2560
	s_cbranch_scc1 .Ltr_loop
	s_cmp_eq_u32 s99, 1
	s_cbranch_scc0 .LBB0_44
	s_mov_b32 s74, s2
	s_branch .Lrms_entry
	s_branch .LBB0_18

.LBB0_1151:
	s_add_u32 s8, s20, 0x10a40000
	s_addc_u32 s9, s21, 0
	s_add_u32 s6, s20, 0x11048000
	s_addc_u32 s7, s21, 0
	s_abs_i32 s0, s29
	v_cvt_f32_u32_e32 v0, s0
	s_sub_i32 s1, s29, s28
	s_add_i32 s4, s1, 0x7f
	s_sub_i32 s1, 0xffffff81, s1
	v_rcp_iflag_f32_e32 v0, v0
	s_xor_b32 s5, s4, s29
	s_max_i32 s1, s4, s1
	s_sub_i32 s4, 0, s0
	v_mul_f32_e32 v0, 0x4f7ffffe, v0
	v_cvt_u32_f32_e32 v0, v0
	s_ashr_i32 s5, s5, 31
	s_waitcnt vmcnt(16)
	v_bfe_u32 v140, v138, 6, 1
	v_bfe_u32 v139, v138, 4, 2
	v_readfirstlane_b32 s10, v0
	s_mul_i32 s4, s4, s10
	s_mul_hi_u32 s4, s10, s4
	s_add_i32 s10, s10, s4
	s_mul_hi_u32 s4, s1, s10
	s_mul_i32 s10, s4, s0
	s_sub_i32 s1, s1, s10
	s_add_i32 s10, s4, 1
	s_sub_i32 s11, s1, s0
	s_cmp_ge_u32 s1, s0
	s_cselect_b32 s4, s10, s4
	s_cselect_b32 s1, s11, s1
	s_add_i32 s10, s4, 1
	s_cmp_ge_u32 s1, s0
	s_cselect_b32 s0, s10, s4
	s_xor_b32 s0, s0, s5
	s_sub_i32 s0, s0, s5
	s_lshl_b32 s56, s0, 3
	s_cmp_ge_i32 s88, s56
	s_mov_b32 s11, 0
	s_cbranch_scc1 .LBB0_1164
	v_lshlrev_b32_e32 v1, 3, v139
	v_and_b32_e32 v0, 15, v138
	v_lshl_or_b32 v1, v140, 7, v1
	s_movk_i32 s4, 0x110
	v_add_u32_e32 v3, 0x100, v138
	v_add_u32_e32 v4, 0x200, v138
	v_add_u32_e32 v5, 0x300, v138
	v_add_u32_e32 v6, 0x400, v138
	v_add_u32_e32 v7, 0x500, v138
	v_add_u32_e32 v8, 0x600, v138
	v_add_u32_e32 v9, 0x700, v138
	v_lshlrev_b32_e32 v2, 4, v138
	v_ashrrev_i32_e32 v141, 4, v138
	v_mad_u32_u24 v142, v0, s4, v1
	v_or_b32_e32 v0, 0x70, v138
	v_ashrrev_i32_e32 v143, 4, v3
	v_ashrrev_i32_e32 v144, 4, v4
	v_ashrrev_i32_e32 v145, 4, v5
	v_ashrrev_i32_e32 v146, 4, v6
	v_ashrrev_i32_e32 v147, 4, v7
	v_ashrrev_i32_e32 v148, 4, v8
	v_ashrrev_i32_e32 v149, 4, v9
	v_and_b32_e32 v128, 0xf0, v2
	v_mov_b32_e32 v129, 0
	v_mul_lo_u32 v2, v141, s4
	s_movk_i32 s5, 0x80
	v_mul_lo_u32 v0, v0, s4
	v_mul_lo_u32 v3, v143, s4
	v_mul_lo_u32 v4, v144, s4
	v_mul_lo_u32 v5, v145, s4
	v_mul_lo_u32 v6, v146, s4
	v_mul_lo_u32 v7, v147, s4
	v_mul_lo_u32 v8, v148, s4
	v_mul_lo_u32 v9, v149, s4
	v_and_b32_e32 v10, 0xffffff80, v138
	v_lshl_add_u64 v[130:131], s[6:7], 0, v[128:129]
	v_cmp_gt_u32_e64 s[0:1], s5, v138
	v_cmp_eq_u32_e64 s[4:5], s5, v10
	s_lshl_b32 s57, s88, 7
	s_lshl_b32 s58, s89, 7
	s_mov_b64 s[46:47], 0
	s_mov_b64 s[12:13], 0x4000
	s_mov_b64 s[14:15], 0x8000
	s_mov_b64 s[16:17], 0xc000
	s_mov_b64 s[30:31], 0x1000
	s_mov_b64 s[34:35], 0x14000
	s_mov_b64 s[36:37], 0x18000
	s_mov_b64 s[38:39], 0x1c000
	s_mov_b64 s[100:101], 0x10000
	v_and_b32_e32 v226, 0x7f, v138
	v_lshlrev_b32_e32 v226, 4, v226
	v_mov_b32_e32 v227, 0
	v_lshrrev_b32_e32 v228, 7, v138
	s_mov_b64 s[40:41], 0x10a50000
	s_mov_b64 s[42:43], 0x10a51000
	v_add_u32_e32 v150, v1, v0
	v_add_u32_e32 v151, v128, v2
	v_add_u32_e32 v152, v128, v3
	v_add_u32_e32 v153, v128, v4
	v_add_u32_e32 v154, v128, v5
	v_add_u32_e32 v155, v128, v6
	v_add_u32_e32 v156, v128, v7
	v_add_u32_e32 v157, v128, v8
	v_add_u32_e32 v158, v128, v9
	s_branch .LBB0_1154

.LBB0_1154:
	s_lshr_b32 s10, s88, 3
	s_mul_i32 s10, s10, s29
	s_add_i32 s10, s10, s28
	v_mov_b32_e32 v2, v181
	s_lshl_b32 s59, s10, 8
	s_lshl_b32 s10, s88, 7
	v_ashrrev_i32_e32 v163, 2, v2
	v_add_u32_e32 v0, s59, v228
	v_lshlrev_b32_e32 v3, 3, v2
	v_ashrrev_i32_e32 v1, 31, v0
	v_bitop3_b32 v4, v3, 24, v2 bitop3:0x48
	v_lshlrev_b32_e32 v165, 4, v2
	s_and_b32 s10, s10, 0x380
	v_lshlrev_b64 v[0:1], 13, v[0:1]
	s_and_b64 vcc, exec, s[46:47]
	v_add_u32_e32 v164, 0x1000, v165
	v_add_u32_e32 v162, 0x2000, v165
	v_add_u32_e32 v161, 0x3000, v165
	v_add_u32_e32 v160, 0x4000, v165
	v_add_u32_e32 v159, 0x5000, v165
	v_lshlrev_b32_e32 v132, 1, v4
	s_cbranch_vccnz .LBB0_1156
	v_lshl_add_u64 v[4:5], s[20:21], 0, v[0:1]
	v_mov_b32_e32 v133, v129
	v_readfirstlane_b32 s24, v165
	v_lshl_add_u64 v[4:5], v[4:5], 0, v[226:227]
	v_add_u32_e32 v6, s10, v163
	s_mov_b32 m0, s24
	v_readfirstlane_b32 s24, v164
	v_ashrrev_i32_e32 v7, 31, v6
	s_barrier
	global_load_lds_dwordx4 v[4:5], off
	v_lshl_add_u64 v[8:9], v[4:5], 0, s[12:13]
	s_mov_b32 m0, s24
	v_readfirstlane_b32 s24, v162
	v_lshlrev_b64 v[6:7], 6, v[6:7]
	global_load_lds_dwordx4 v[8:9], off
	v_lshl_add_u64 v[8:9], v[4:5], 0, s[14:15]
	s_mov_b32 m0, s24
	v_readfirstlane_b32 s24, v161
	v_lshl_add_u64 v[6:7], s[8:9], 0, v[6:7]
	global_load_lds_dwordx4 v[8:9], off
	v_lshl_add_u64 v[4:5], v[4:5], 0, s[16:17]
	s_mov_b32 m0, s24
	v_readfirstlane_b32 s24, v160
	v_lshl_add_u64 v[6:7], v[6:7], 0, v[132:133]
	global_load_lds_dwordx4 v[4:5], off
	s_mov_b32 m0, s24
	v_readfirstlane_b32 s24, v159
	global_load_lds_dwordx4 v[6:7], off
	v_lshl_add_u64 v[4:5], v[6:7], 0, s[30:31]
	s_mov_b32 m0, s24
	s_nop 0
	global_load_lds_dwordx4 v[4:5], off
.LBB0_1156:
	v_xor_b32_e32 v3, v3, v2
	v_lshlrev_b32_e32 v2, 6, v2
	v_and_b32_e32 v168, 0x1000, v2
	v_and_b32_e32 v166, 0x3c0, v2
	v_and_b32_e32 v167, 0xffffe000, v2
	v_lshlrev_b32_e32 v2, 1, v3
	v_and_b32_e32 v128, 48, v2
	s_and_b32 s24, s57, 0x380
	v_lshl_add_u64 v[0:1], v[0:1], 0, v[226:227]
	v_lshl_add_u64 v[134:135], s[20:21], 0, v[0:1]
	v_add_u32_e32 v0, s24, v163
	v_ashrrev_i32_e32 v1, 31, v0
	v_lshlrev_b64 v[0:1], 6, v[0:1]
	v_or_b32_e32 v0, v0, v128
	v_lshl_add_u64 v[136:137], s[20:21], 0, v[0:1]
	v_mov_b32_e32 v0, 0
	v_and_b32_e32 v133, 48, v3
	s_mov_b32 s46, 1
	s_mov_b64 s[44:45], 0
	v_mov_b32_e32 v1, v0
	v_mov_b32_e32 v2, v0
	v_mov_b32_e32 v3, v0
	v_mov_b32_e32 v4, v0
	v_mov_b32_e32 v5, v0
	v_mov_b32_e32 v6, v0
	v_mov_b32_e32 v7, v0
	v_mov_b32_e32 v8, v0
	v_mov_b32_e32 v9, v0
	v_mov_b32_e32 v10, v0
	v_mov_b32_e32 v11, v0
	v_mov_b32_e32 v12, v0
	v_mov_b32_e32 v13, v0
	v_mov_b32_e32 v14, v0
	v_mov_b32_e32 v15, v0
	v_mov_b32_e32 v16, v0
	v_mov_b32_e32 v17, v0
	v_mov_b32_e32 v18, v0
	v_mov_b32_e32 v19, v0
	v_mov_b32_e32 v20, v0
	v_mov_b32_e32 v21, v0
	v_mov_b32_e32 v22, v0
	v_mov_b32_e32 v23, v0
	v_mov_b32_e32 v24, v0
	v_mov_b32_e32 v25, v0
	v_mov_b32_e32 v26, v0
	v_mov_b32_e32 v27, v0
	v_mov_b32_e32 v28, v0
	v_mov_b32_e32 v29, v0
	v_mov_b32_e32 v30, v0
	v_mov_b32_e32 v31, v0
	v_mov_b32_e32 v32, v0
	v_mov_b32_e32 v33, v0
	v_mov_b32_e32 v34, v0
	v_mov_b32_e32 v35, v0
	v_mov_b32_e32 v36, v0
	v_mov_b32_e32 v37, v0
	v_mov_b32_e32 v38, v0
	v_mov_b32_e32 v39, v0
	v_mov_b32_e32 v40, v0
	v_mov_b32_e32 v41, v0
	v_mov_b32_e32 v42, v0
	v_mov_b32_e32 v43, v0
	v_mov_b32_e32 v44, v0
	v_mov_b32_e32 v45, v0
	v_mov_b32_e32 v46, v0
	v_mov_b32_e32 v47, v0
	v_mov_b32_e32 v48, v0
	v_mov_b32_e32 v49, v0
	v_mov_b32_e32 v50, v0
	v_mov_b32_e32 v51, v0
	v_mov_b32_e32 v52, v0
	v_mov_b32_e32 v53, v0
	v_mov_b32_e32 v54, v0
	v_mov_b32_e32 v55, v0
	v_mov_b32_e32 v56, v0
	v_mov_b32_e32 v57, v0
	v_mov_b32_e32 v58, v0
	v_mov_b32_e32 v59, v0
	v_mov_b32_e32 v60, v0
	v_mov_b32_e32 v61, v0
	v_mov_b32_e32 v62, v0
	v_mov_b32_e32 v63, v0
	v_mov_b32_e32 v64, v0
	v_mov_b32_e32 v65, v0
	v_mov_b32_e32 v66, v0
	v_mov_b32_e32 v67, v0
	v_mov_b32_e32 v68, v0
	v_mov_b32_e32 v69, v0
	v_mov_b32_e32 v70, v0
	v_mov_b32_e32 v71, v0
	v_mov_b32_e32 v72, v0
	v_mov_b32_e32 v73, v0
	v_mov_b32_e32 v74, v0
	v_mov_b32_e32 v75, v0
	v_mov_b32_e32 v76, v0
	v_mov_b32_e32 v77, v0
	v_mov_b32_e32 v78, v0
	v_mov_b32_e32 v79, v0
	v_mov_b32_e32 v80, v0
	v_mov_b32_e32 v81, v0
	v_mov_b32_e32 v82, v0
	v_mov_b32_e32 v83, v0
	v_mov_b32_e32 v84, v0
	v_mov_b32_e32 v85, v0
	v_mov_b32_e32 v86, v0
	v_mov_b32_e32 v87, v0
	v_mov_b32_e32 v88, v0
	v_mov_b32_e32 v89, v0
	v_mov_b32_e32 v90, v0
	v_mov_b32_e32 v91, v0
	v_mov_b32_e32 v92, v0
	v_mov_b32_e32 v93, v0
	v_mov_b32_e32 v94, v0
	v_mov_b32_e32 v95, v0
	v_mov_b32_e32 v96, v0
	v_mov_b32_e32 v97, v0
	v_mov_b32_e32 v98, v0
	v_mov_b32_e32 v99, v0
	v_mov_b32_e32 v100, v0
	v_mov_b32_e32 v101, v0
	v_mov_b32_e32 v102, v0
	v_mov_b32_e32 v103, v0
	v_mov_b32_e32 v104, v0
	v_mov_b32_e32 v105, v0
	v_mov_b32_e32 v106, v0
	v_mov_b32_e32 v107, v0
	v_mov_b32_e32 v108, v0
	v_mov_b32_e32 v109, v0
	v_mov_b32_e32 v110, v0
	v_mov_b32_e32 v111, v0
	v_mov_b32_e32 v112, v0
	v_mov_b32_e32 v113, v0
	v_mov_b32_e32 v114, v0
	v_mov_b32_e32 v115, v0
	v_mov_b32_e32 v116, v0
	v_mov_b32_e32 v117, v0
	v_mov_b32_e32 v118, v0
	v_mov_b32_e32 v119, v0
	v_mov_b32_e32 v120, v0
	v_mov_b32_e32 v121, v0
	v_mov_b32_e32 v122, v0
	v_mov_b32_e32 v123, v0
	v_mov_b32_e32 v124, v0
	v_mov_b32_e32 v125, v0
	v_mov_b32_e32 v126, v0
	v_mov_b32_e32 v127, v0
	s_waitcnt vmcnt(0) lgkmcnt(0)
	s_barrier
.LBB0_1157:
	s_lshl_b64 s[98:99], s[44:45], 10
	s_bitcmp1_b32 s46, 0
	s_cselect_b32 s24, 0x6000, 0
	v_add_u32_e32 v128, s24, v165
	v_lshl_add_u64 v[170:171], v[134:135], 0, s[98:99]
	v_readfirstlane_b32 s24, v128
	v_add_u32_e32 v169, 0x1000, v128
	v_lshl_add_u64 v[172:173], v[170:171], 0, s[100:101]
	s_mov_b32 m0, s24
	v_readfirstlane_b32 s24, v169
	v_add_u32_e32 v169, 0x2000, v128
	global_load_lds_dwordx4 v[172:173], off
	v_lshl_add_u64 v[172:173], v[170:171], 0, s[34:35]
	s_mov_b32 m0, s24
	v_readfirstlane_b32 s24, v169
	v_add_u32_e32 v169, 0x3000, v128
	global_load_lds_dwordx4 v[172:173], off
	v_lshl_add_u64 v[172:173], v[170:171], 0, s[36:37]
	s_mov_b32 m0, s24
	v_readfirstlane_b32 s24, v169
	global_load_lds_dwordx4 v[172:173], off
	v_lshl_add_u64 v[170:171], v[170:171], 0, s[38:39]
	s_mov_b32 m0, s24
	v_add_u32_e32 v169, 0x4000, v128
	global_load_lds_dwordx4 v[170:171], off
	v_lshl_add_u64 v[170:171], v[136:137], 0, s[98:99]
	v_readfirstlane_b32 s24, v169
	v_add_u32_e32 v128, 0x5000, v128
	v_lshl_add_u64 v[172:173], v[170:171], 0, s[40:41]
	s_mov_b32 m0, s24
	v_readfirstlane_b32 s24, v128
	global_load_lds_dwordx4 v[172:173], off
	v_lshl_add_u64 v[170:171], v[170:171], 0, s[42:43]
	s_mov_b32 m0, s24
	s_nop 0
	global_load_lds_dwordx4 v[170:171], off
	s_cselect_b32 s24, 0, 0x6000
	v_or_b32_e32 v128, s24, v168
	v_add3_u32 v128, v128, v166, v133
	ds_read_b128 v[170:173], v128 offset:16384
	ds_read_b128 v[174:177], v128 offset:17408
	ds_read_b128 v[184:187], v128 offset:18432
	ds_read_b128 v[188:191], v128 offset:19456
	v_add_u32_e32 v128, s24, v167
	v_add3_u32 v128, v128, v166, v133
	ds_read_b128 v[192:195], v128
	ds_read_b128 v[196:199], v128 offset:1024
	ds_read_b128 v[200:203], v128 offset:2048
	ds_read_b128 v[204:207], v128 offset:3072
	ds_read_b128 v[208:211], v128 offset:4096
	ds_read_b128 v[212:215], v128 offset:5120
	ds_read_b128 v[216:219], v128 offset:6144
	ds_read_b128 v[220:223], v128 offset:7168
	s_setprio 1
	s_waitcnt lgkmcnt(0)
	v_mfma_f32_16x16x32_bf16 v[124:127], v[170:173], v[192:195], v[124:127]
	v_mfma_f32_16x16x32_bf16 v[120:123], v[174:177], v[192:195], v[120:123]
	v_mfma_f32_16x16x32_bf16 v[116:119], v[184:187], v[192:195], v[116:119]
	v_mfma_f32_16x16x32_bf16 v[112:115], v[188:191], v[192:195], v[112:115]
	v_mfma_f32_16x16x32_bf16 v[108:111], v[170:173], v[196:199], v[108:111]
	v_mfma_f32_16x16x32_bf16 v[104:107], v[174:177], v[196:199], v[104:107]
	v_mfma_f32_16x16x32_bf16 v[100:103], v[184:187], v[196:199], v[100:103]
	v_mfma_f32_16x16x32_bf16 v[96:99], v[188:191], v[196:199], v[96:99]
	v_mfma_f32_16x16x32_bf16 v[92:95], v[170:173], v[200:203], v[92:95]
	v_mfma_f32_16x16x32_bf16 v[88:91], v[174:177], v[200:203], v[88:91]
	v_mfma_f32_16x16x32_bf16 v[84:87], v[184:187], v[200:203], v[84:87]
	v_mfma_f32_16x16x32_bf16 v[80:83], v[188:191], v[200:203], v[80:83]
	v_mfma_f32_16x16x32_bf16 v[76:79], v[170:173], v[204:207], v[76:79]
	v_mfma_f32_16x16x32_bf16 v[72:75], v[174:177], v[204:207], v[72:75]
	v_mfma_f32_16x16x32_bf16 v[68:71], v[184:187], v[204:207], v[68:71]
	v_mfma_f32_16x16x32_bf16 v[64:67], v[188:191], v[204:207], v[64:67]
	v_mfma_f32_16x16x32_bf16 v[60:63], v[170:173], v[208:211], v[60:63]
	v_mfma_f32_16x16x32_bf16 v[56:59], v[174:177], v[208:211], v[56:59]
	v_mfma_f32_16x16x32_bf16 v[52:55], v[184:187], v[208:211], v[52:55]
	v_mfma_f32_16x16x32_bf16 v[48:51], v[188:191], v[208:211], v[48:51]
	v_mfma_f32_16x16x32_bf16 v[44:47], v[170:173], v[212:215], v[44:47]
	v_mfma_f32_16x16x32_bf16 v[40:43], v[174:177], v[212:215], v[40:43]
	v_mfma_f32_16x16x32_bf16 v[36:39], v[184:187], v[212:215], v[36:39]
	v_mfma_f32_16x16x32_bf16 v[32:35], v[188:191], v[212:215], v[32:35]
	v_mfma_f32_16x16x32_bf16 v[28:31], v[170:173], v[216:219], v[28:31]
	v_mfma_f32_16x16x32_bf16 v[24:27], v[174:177], v[216:219], v[24:27]
	v_mfma_f32_16x16x32_bf16 v[20:23], v[184:187], v[216:219], v[20:23]
	v_mfma_f32_16x16x32_bf16 v[16:19], v[188:191], v[216:219], v[16:19]
	v_mfma_f32_16x16x32_bf16 v[12:15], v[170:173], v[220:223], v[12:15]
	v_mfma_f32_16x16x32_bf16 v[8:11], v[174:177], v[220:223], v[8:11]
	v_mfma_f32_16x16x32_bf16 v[4:7], v[184:187], v[220:223], v[4:7]
	v_mfma_f32_16x16x32_bf16 v[0:3], v[188:191], v[220:223], v[0:3]
	s_setprio 0
	s_add_u32 s44, s44, 64
	s_addc_u32 s45, s45, 0
	s_add_i32 s46, s46, 1
	s_cmpk_eq_i32 s44, 0x7c0
	s_waitcnt vmcnt(0)
	s_barrier
	s_cbranch_scc0 .LBB0_1157
	s_add_i32 s88, s88, s89
	s_cmp_ge_i32 s88, s56
	s_cselect_b64 s[44:45], -1, 0
	s_cmp_lt_i32 s88, s56
	v_add3_u32 v128, v168, v166, v133
	ds_read_b128 v[134:137], v128 offset:40960
	ds_read_b128 v[168:171], v128 offset:41984
	ds_read_b128 v[172:175], v128 offset:43008
	ds_read_b128 v[176:179], v128 offset:44032
	v_add3_u32 v128, v167, v166, v133
	ds_read_b128 v[184:187], v128 offset:24576
	ds_read_b128 v[188:191], v128 offset:25600
	ds_read_b128 v[192:195], v128 offset:26624
	ds_read_b128 v[196:199], v128 offset:27648
	ds_read_b128 v[200:203], v128 offset:28672
	ds_read_b128 v[204:207], v128 offset:29696
	ds_read_b128 v[208:211], v128 offset:30720
	ds_read_b128 v[212:215], v128 offset:31744
	s_setprio 1
	s_waitcnt lgkmcnt(7)
	v_mfma_f32_16x16x32_bf16 v[124:127], v[134:137], v[184:187], v[124:127]
	v_mfma_f32_16x16x32_bf16 v[120:123], v[168:171], v[184:187], v[120:123]
	v_mfma_f32_16x16x32_bf16 v[116:119], v[172:175], v[184:187], v[116:119]
	v_mfma_f32_16x16x32_bf16 v[112:115], v[176:179], v[184:187], v[112:115]
	s_waitcnt lgkmcnt(6)
	v_mfma_f32_16x16x32_bf16 v[108:111], v[134:137], v[188:191], v[108:111]
	v_mfma_f32_16x16x32_bf16 v[104:107], v[168:171], v[188:191], v[104:107]
	v_mfma_f32_16x16x32_bf16 v[100:103], v[172:175], v[188:191], v[100:103]
	v_mfma_f32_16x16x32_bf16 v[96:99], v[176:179], v[188:191], v[96:99]
	s_waitcnt lgkmcnt(5)
	v_mfma_f32_16x16x32_bf16 v[92:95], v[134:137], v[192:195], v[92:95]
	v_mfma_f32_16x16x32_bf16 v[88:91], v[168:171], v[192:195], v[88:91]
	v_mfma_f32_16x16x32_bf16 v[84:87], v[172:175], v[192:195], v[84:87]
	v_mfma_f32_16x16x32_bf16 v[80:83], v[176:179], v[192:195], v[80:83]
	s_waitcnt lgkmcnt(4)
	v_mfma_f32_16x16x32_bf16 v[76:79], v[134:137], v[196:199], v[76:79]
	v_mfma_f32_16x16x32_bf16 v[72:75], v[168:171], v[196:199], v[72:75]
	v_mfma_f32_16x16x32_bf16 v[68:71], v[172:175], v[196:199], v[68:71]
	v_mfma_f32_16x16x32_bf16 v[64:67], v[176:179], v[196:199], v[64:67]
	s_waitcnt lgkmcnt(3)
	v_mfma_f32_16x16x32_bf16 v[60:63], v[134:137], v[200:203], v[60:63]
	v_mfma_f32_16x16x32_bf16 v[56:59], v[168:171], v[200:203], v[56:59]
	v_mfma_f32_16x16x32_bf16 v[52:55], v[172:175], v[200:203], v[52:55]
	v_mfma_f32_16x16x32_bf16 v[48:51], v[176:179], v[200:203], v[48:51]
	s_waitcnt lgkmcnt(2)
	v_mfma_f32_16x16x32_bf16 v[44:47], v[134:137], v[204:207], v[44:47]
	v_mfma_f32_16x16x32_bf16 v[40:43], v[168:171], v[204:207], v[40:43]
	v_mfma_f32_16x16x32_bf16 v[36:39], v[172:175], v[204:207], v[36:39]
	v_mfma_f32_16x16x32_bf16 v[32:35], v[176:179], v[204:207], v[32:35]
	s_waitcnt lgkmcnt(1)
	v_mfma_f32_16x16x32_bf16 v[28:31], v[134:137], v[208:211], v[28:31]
	v_mfma_f32_16x16x32_bf16 v[24:27], v[168:171], v[208:211], v[24:27]
	v_mfma_f32_16x16x32_bf16 v[20:23], v[172:175], v[208:211], v[20:23]
	v_mfma_f32_16x16x32_bf16 v[16:19], v[176:179], v[208:211], v[16:19]
	s_waitcnt lgkmcnt(0)
	v_mfma_f32_16x16x32_bf16 v[12:15], v[134:137], v[212:215], v[12:15]
	v_mfma_f32_16x16x32_bf16 v[8:11], v[168:171], v[212:215], v[8:11]
	v_mfma_f32_16x16x32_bf16 v[4:7], v[172:175], v[212:215], v[4:7]
	v_mfma_f32_16x16x32_bf16 v[0:3], v[176:179], v[212:215], v[0:3]
	s_setprio 0
	s_barrier
	s_cbranch_scc0 .LBB0_1160
	s_lshr_b32 s24, s88, 3
	s_mul_i32 s24, s24, s29
	s_add_i32 s24, s24, s28
	s_lshl_b32 s25, s88, 7
	s_and_b32 s25, s25, 0x380
	v_lshl_add_u32 v134, s24, 8, v228
	v_ashrrev_i32_e32 v135, 31, v134
	v_add_u32_e32 v136, s25, v163
	v_lshlrev_b64 v[134:135], 13, v[134:135]
	v_ashrrev_i32_e32 v137, 31, v136
	v_lshl_add_u64 v[134:135], s[20:21], 0, v[134:135]
	v_mov_b32_e32 v133, v129
	v_lshlrev_b64 v[136:137], 6, v[136:137]
	v_readfirstlane_b32 s24, v165
	v_lshl_add_u64 v[134:135], v[134:135], 0, v[226:227]
	v_lshl_add_u64 v[136:137], s[8:9], 0, v[136:137]
	s_mov_b32 m0, s24
	v_readfirstlane_b32 s24, v164
	v_lshl_add_u64 v[132:133], v[136:137], 0, v[132:133]
	global_load_lds_dwordx4 v[134:135], off
	v_lshl_add_u64 v[136:137], v[134:135], 0, s[12:13]
	s_mov_b32 m0, s24
	v_readfirstlane_b32 s24, v162
	global_load_lds_dwordx4 v[136:137], off
	v_lshl_add_u64 v[136:137], v[134:135], 0, s[14:15]
	s_mov_b32 m0, s24
	v_readfirstlane_b32 s24, v161
	global_load_lds_dwordx4 v[136:137], off
	v_lshl_add_u64 v[134:135], v[134:135], 0, s[16:17]
	s_mov_b32 m0, s24
	v_readfirstlane_b32 s24, v160
	global_load_lds_dwordx4 v[134:135], off
	s_mov_b32 m0, s24
	v_readfirstlane_b32 s24, v159
	global_load_lds_dwordx4 v[132:133], off
	v_lshl_add_u64 v[132:133], v[132:133], 0, s[30:31]
	s_mov_b32 m0, s24
	s_nop 0
	global_load_lds_dwordx4 v[132:133], off

.LBB0_1164:
	s_cmp_gt_i32 s2, 63
	s_cbranch_scc1 .LBB0_1168
	v_lshlrev_b32_e32 v0, 8, v140
	v_mov_b32_e32 v1, 0
	v_lshl_add_u64 v[2:3], s[20:21], 0, v[0:1]
	v_lshlrev_b32_e32 v0, 4, v139
	v_lshl_add_u64 v[2:3], v[2:3], 0, v[0:1]
	s_mov_b64 s[0:1], 0x1d754000
	v_and_b32_e32 v4, 0xffffff8f, v138
	v_lshl_add_u64 v[2:3], v[2:3], 0, s[0:1]
	s_lshl_b32 s80, s2, 4
	s_lshl_b32 s81, s22, 4
	s_mov_b32 s1, 0
	s_mov_b64 s[4:5], 0x10180000
	s_mov_b64 s[10:11], 0x20000
	s_mov_b64 s[12:13], 0x10000040
	s_mov_b64 s[14:15], 0x10080040
	s_mov_b64 s[16:17], 0x10100040
	s_mov_b64 s[28:29], 0x10180040
	s_mov_b64 s[30:31], 0x11000
	s_mov_b64 s[100:101], 0x1000
	s_movk_i32 s82, 0x13c0
	s_movk_i32 s83, 0xe3c0
	s_mov_b64 s[34:35], 0x10000080
	s_mov_b64 s[36:37], 0x10080080
	s_mov_b64 s[38:39], 0x10100080
	s_mov_b64 s[40:41], 0x10180080
	s_mov_b64 s[42:43], 0x20000
	s_mov_b64 s[44:45], 0x21000
	s_mov_b64 s[46:47], 0x100000c0
	s_mov_b64 s[56:57], 0x100800c0
	s_mov_b64 s[58:59], 0x101000c0
	s_mov_b64 s[60:61], 0x101800c0
	s_mov_b64 s[62:63], 0x30000
	s_mov_b64 s[64:65], 0x31000
	s_mov_b64 s[66:67], 0x10000
	s_mov_b32 s84, 0x10000
	s_mov_b32 s85, 0x20000
	s_mov_b64 s[68:69], 0x30000
	s_mov_b32 s86, 0x30000
	s_mov_b64 s[70:71], 0x40000
	s_mov_b32 s87, 0x40000
	s_mov_b64 s[72:73], 0x50000
	s_mov_b32 s88, 0x50000
	s_mov_b64 s[74:75], 0x60000
	s_mov_b32 s89, 0x60000
	s_mov_b64 s[76:77], 0x70000
	s_mov_b32 s90, s2
.LBB0_1166:
	v_mov_b32_e32 v5, v181
	s_and_b32 s78, s80, 0xffffff80
	v_ashrrev_i32_e32 v6, 2, v5
	v_ashrrev_i32_e32 v7, 31, v6
	v_lshlrev_b64 v[8:9], 13, v[6:7]
	v_add_u32_e32 v6, s78, v6
	v_lshlrev_b32_e32 v10, 3, v5
	v_ashrrev_i32_e32 v7, 31, v6
	v_bitop3_b32 v0, v10, 24, v5 bitop3:0x48
	v_lshlrev_b64 v[6:7], 6, v[6:7]
	v_lshl_add_u64 v[8:9], s[20:21], 0, v[8:9]
	v_lshlrev_b32_e32 v0, 1, v0
	s_lshl_b32 s0, s90, 8
	v_lshl_add_u64 v[6:7], s[8:9], 0, v[6:7]
	v_lshl_add_u64 v[8:9], v[8:9], 0, v[0:1]
	s_and_b32 s0, s0, 0x700
	s_lshl_b64 s[98:99], s[0:1], 10
	v_lshl_add_u64 v[6:7], v[6:7], 0, v[0:1]
	v_lshlrev_b32_e32 v0, 4, v5
	v_lshl_add_u64 v[178:179], v[8:9], 0, s[0:1]
	s_mov_b64 s[24:25], 0x10000000
	v_readfirstlane_b32 s33, v0
	v_lshl_add_u64 v[8:9], v[178:179], 0, s[24:25]
	s_mov_b32 m0, s33
	s_waitcnt vmcnt(0)
	s_barrier
	global_load_lds_dwordx4 v[8:9], off
	v_add_u32_e32 v8, 0x1000, v0
	s_mov_b64 s[24:25], 0x10080000
	v_readfirstlane_b32 s79, v8
	v_lshl_add_u64 v[188:189], v[6:7], 0, s[98:99]
	v_lshl_add_u64 v[6:7], v[178:179], 0, s[24:25]
	s_mov_b32 m0, s79
	s_mov_b64 s[24:25], 0x10100000
	v_add_u32_e32 v8, 0x2000, v0
	global_load_lds_dwordx4 v[6:7], off
	v_lshl_add_u64 v[6:7], v[178:179], 0, s[24:25]
	v_readfirstlane_b32 s24, v8
	v_add_u32_e32 v8, 0x3000, v0
	s_mov_b32 m0, s24
	v_readfirstlane_b32 s25, v8
	global_load_lds_dwordx4 v[6:7], off
	v_lshl_add_u64 v[6:7], v[178:179], 0, s[4:5]
	s_mov_b32 m0, s25
	v_add_u32_e32 v8, 0x5000, v0
	global_load_lds_dwordx4 v[6:7], off
	v_add_u32_e32 v6, 0x4000, v0
	v_readfirstlane_b32 s92, v8
	v_readfirstlane_b32 s91, v6
	s_mov_b32 m0, s91
	v_add_u32_e32 v8, 0x6000, v0
	global_load_lds_dwordx4 v[188:189], off
	v_lshl_add_u64 v[6:7], v[188:189], 0, s[100:101]
	s_mov_b32 m0, s92
	v_readfirstlane_b32 s93, v8
	v_add_u32_e32 v8, 0x7000, v0
	global_load_lds_dwordx4 v[6:7], off
	v_lshl_add_u64 v[6:7], v[178:179], 0, s[12:13]
	s_mov_b32 m0, s93
	v_readfirstlane_b32 s94, v8
	v_add_u32_e32 v8, 0x8000, v0
	s_waitcnt vmcnt(0) lgkmcnt(0)
	s_barrier
	global_load_lds_dwordx4 v[6:7], off
	v_lshl_add_u64 v[6:7], v[178:179], 0, s[14:15]
	s_mov_b32 m0, s94
	v_readfirstlane_b32 s95, v8
	v_add_u32_e32 v8, 0x9000, v0
	global_load_lds_dwordx4 v[6:7], off
	v_lshl_add_u64 v[6:7], v[178:179], 0, s[16:17]
	s_mov_b32 m0, s95
	v_readfirstlane_b32 s96, v8
	v_add_u32_e32 v8, 0xa000, v0
	global_load_lds_dwordx4 v[6:7], off
	v_lshl_add_u64 v[6:7], v[178:179], 0, s[28:29]
	s_mov_b32 m0, s96
	v_readfirstlane_b32 s97, v8
	v_add_u32_e32 v0, 0xb000, v0
	global_load_lds_dwordx4 v[6:7], off
	v_lshl_add_u64 v[6:7], v[188:189], 0, s[66:67]
	s_mov_b32 m0, s97
	v_readfirstlane_b32 s18, v0
	global_load_lds_dwordx4 v[6:7], off
	v_lshl_add_u64 v[6:7], v[188:189], 0, s[30:31]
	s_mov_b32 m0, s18
	v_bitop3_b32 v0, v10, 48, v5 bitop3:0x48
	global_load_lds_dwordx4 v[6:7], off
	v_lshlrev_b32_e32 v5, 6, v5
	v_and_or_b32 v190, v5, s82, v0
	v_and_or_b32 v0, v5, s83, v0
	ds_read_b128 v[6:9], v190 offset:16384
	ds_read_b128 v[10:13], v190 offset:17408
	ds_read_b128 v[14:17], v190 offset:18432
	ds_read_b128 v[18:21], v190 offset:19456
	ds_read_b128 v[22:25], v0
	ds_read_b128 v[26:29], v0 offset:1024
	ds_read_b128 v[30:33], v0 offset:2048
	ds_read_b128 v[34:37], v0 offset:3072
	ds_read_b128 v[38:41], v0 offset:4096
	ds_read_b128 v[42:45], v0 offset:5120
	ds_read_b128 v[46:49], v0 offset:6144
	ds_read_b128 v[50:53], v0 offset:7168
	s_setprio 1
	s_waitcnt lgkmcnt(0)
	v_mfma_f32_16x16x32_bf16 v[54:57], v[6:9], v[22:25], 0
	v_mfma_f32_16x16x32_bf16 v[58:61], v[10:13], v[22:25], 0
	v_mfma_f32_16x16x32_bf16 v[62:65], v[14:17], v[22:25], 0
	v_mfma_f32_16x16x32_bf16 v[22:25], v[18:21], v[22:25], 0
	v_mfma_f32_16x16x32_bf16 v[66:69], v[6:9], v[26:29], 0
	v_mfma_f32_16x16x32_bf16 v[70:73], v[10:13], v[26:29], 0
	v_mfma_f32_16x16x32_bf16 v[74:77], v[14:17], v[26:29], 0
	v_mfma_f32_16x16x32_bf16 v[26:29], v[18:21], v[26:29], 0
	v_mfma_f32_16x16x32_bf16 v[78:81], v[6:9], v[30:33], 0
	v_mfma_f32_16x16x32_bf16 v[82:85], v[10:13], v[30:33], 0
	v_mfma_f32_16x16x32_bf16 v[86:89], v[14:17], v[30:33], 0
	v_mfma_f32_16x16x32_bf16 v[30:33], v[18:21], v[30:33], 0
	v_mfma_f32_16x16x32_bf16 v[90:93], v[6:9], v[34:37], 0
	v_mfma_f32_16x16x32_bf16 v[94:97], v[10:13], v[34:37], 0
	v_mfma_f32_16x16x32_bf16 v[98:101], v[14:17], v[34:37], 0
	v_mfma_f32_16x16x32_bf16 v[34:37], v[18:21], v[34:37], 0
	v_mfma_f32_16x16x32_bf16 v[102:105], v[6:9], v[38:41], 0
	v_mfma_f32_16x16x32_bf16 v[106:109], v[10:13], v[38:41], 0
	v_mfma_f32_16x16x32_bf16 v[110:113], v[14:17], v[38:41], 0
	v_mfma_f32_16x16x32_bf16 v[38:41], v[18:21], v[38:41], 0
	v_mfma_f32_16x16x32_bf16 v[114:117], v[6:9], v[42:45], 0
	v_mfma_f32_16x16x32_bf16 v[118:121], v[10:13], v[42:45], 0
	v_mfma_f32_16x16x32_bf16 v[122:125], v[14:17], v[42:45], 0
	v_mfma_f32_16x16x32_bf16 v[42:45], v[18:21], v[42:45], 0
	v_mfma_f32_16x16x32_bf16 v[126:129], v[6:9], v[46:49], 0
	v_mfma_f32_16x16x32_bf16 v[130:133], v[10:13], v[46:49], 0
	v_mfma_f32_16x16x32_bf16 v[134:137], v[14:17], v[46:49], 0
	v_mfma_f32_16x16x32_bf16 v[46:49], v[18:21], v[46:49], 0
	v_mfma_f32_16x16x32_bf16 v[6:9], v[6:9], v[50:53], 0
	v_mfma_f32_16x16x32_bf16 v[10:13], v[10:13], v[50:53], 0
	v_mfma_f32_16x16x32_bf16 v[14:17], v[14:17], v[50:53], 0
	v_mfma_f32_16x16x32_bf16 v[18:21], v[18:21], v[50:53], 0
	s_setprio 0
	s_mov_b32 m0, s33
	v_lshl_add_u64 v[50:51], v[178:179], 0, s[34:35]
	s_waitcnt vmcnt(0)
	s_barrier
	global_load_lds_dwordx4 v[50:51], off
	v_lshl_add_u64 v[50:51], v[178:179], 0, s[36:37]
	s_mov_b32 m0, s79
	s_nop 0
	global_load_lds_dwordx4 v[50:51], off
	v_lshl_add_u64 v[50:51], v[178:179], 0, s[38:39]
	s_mov_b32 m0, s24
	s_nop 0
	global_load_lds_dwordx4 v[50:51], off
	v_lshl_add_u64 v[50:51], v[178:179], 0, s[40:41]
	s_mov_b32 m0, s25
	s_nop 0
	global_load_lds_dwordx4 v[50:51], off
	v_lshl_add_u64 v[50:51], v[188:189], 0, s[42:43]
	s_mov_b32 m0, s91
	s_nop 0
	global_load_lds_dwordx4 v[50:51], off
	v_lshl_add_u64 v[50:51], v[188:189], 0, s[44:45]
	s_mov_b32 m0, s92
	s_nop 0
	global_load_lds_dwordx4 v[50:51], off
	ds_read_b128 v[50:53], v190 offset:40960
	ds_read_b128 v[138:141], v190 offset:41984
	ds_read_b128 v[142:145], v190 offset:43008
	ds_read_b128 v[146:149], v190 offset:44032
	ds_read_b128 v[150:153], v0 offset:24576
	ds_read_b128 v[154:157], v0 offset:25600
	ds_read_b128 v[158:161], v0 offset:26624
	ds_read_b128 v[162:165], v0 offset:27648
	ds_read_b128 v[166:169], v0 offset:28672
	ds_read_b128 v[170:173], v0 offset:29696
	ds_read_b128 v[174:177], v0 offset:30720
	ds_read_b128 v[184:187], v0 offset:31744
	s_setprio 1
	s_waitcnt lgkmcnt(0)
	v_mfma_f32_16x16x32_bf16 v[54:57], v[50:53], v[150:153], v[54:57]
	v_mfma_f32_16x16x32_bf16 v[58:61], v[138:141], v[150:153], v[58:61]
	v_mfma_f32_16x16x32_bf16 v[62:65], v[142:145], v[150:153], v[62:65]
	v_mfma_f32_16x16x32_bf16 v[22:25], v[146:149], v[150:153], v[22:25]
	v_mfma_f32_16x16x32_bf16 v[66:69], v[50:53], v[154:157], v[66:69]
	v_mfma_f32_16x16x32_bf16 v[70:73], v[138:141], v[154:157], v[70:73]
	v_mfma_f32_16x16x32_bf16 v[74:77], v[142:145], v[154:157], v[74:77]
	v_mfma_f32_16x16x32_bf16 v[26:29], v[146:149], v[154:157], v[26:29]
	v_mfma_f32_16x16x32_bf16 v[78:81], v[50:53], v[158:161], v[78:81]
	v_mfma_f32_16x16x32_bf16 v[82:85], v[138:141], v[158:161], v[82:85]
	v_mfma_f32_16x16x32_bf16 v[86:89], v[142:145], v[158:161], v[86:89]
	v_mfma_f32_16x16x32_bf16 v[30:33], v[146:149], v[158:161], v[30:33]
	v_mfma_f32_16x16x32_bf16 v[90:93], v[50:53], v[162:165], v[90:93]
	v_mfma_f32_16x16x32_bf16 v[94:97], v[138:141], v[162:165], v[94:97]
	v_mfma_f32_16x16x32_bf16 v[98:101], v[142:145], v[162:165], v[98:101]
	v_mfma_f32_16x16x32_bf16 v[34:37], v[146:149], v[162:165], v[34:37]
	v_mfma_f32_16x16x32_bf16 v[102:105], v[50:53], v[166:169], v[102:105]
	v_mfma_f32_16x16x32_bf16 v[106:109], v[138:141], v[166:169], v[106:109]
	v_mfma_f32_16x16x32_bf16 v[110:113], v[142:145], v[166:169], v[110:113]
	v_mfma_f32_16x16x32_bf16 v[38:41], v[146:149], v[166:169], v[38:41]
	v_mfma_f32_16x16x32_bf16 v[114:117], v[50:53], v[170:173], v[114:117]
	v_mfma_f32_16x16x32_bf16 v[118:121], v[138:141], v[170:173], v[118:121]
	v_mfma_f32_16x16x32_bf16 v[122:125], v[142:145], v[170:173], v[122:125]
	v_mfma_f32_16x16x32_bf16 v[42:45], v[146:149], v[170:173], v[42:45]
	v_mfma_f32_16x16x32_bf16 v[126:129], v[50:53], v[174:177], v[126:129]
	v_mfma_f32_16x16x32_bf16 v[130:133], v[138:141], v[174:177], v[130:133]
	v_mfma_f32_16x16x32_bf16 v[134:137], v[142:145], v[174:177], v[134:137]
	v_mfma_f32_16x16x32_bf16 v[46:49], v[146:149], v[174:177], v[46:49]
	v_mfma_f32_16x16x32_bf16 v[6:9], v[50:53], v[184:187], v[6:9]
	v_mfma_f32_16x16x32_bf16 v[10:13], v[138:141], v[184:187], v[10:13]
	v_mfma_f32_16x16x32_bf16 v[14:17], v[142:145], v[184:187], v[14:17]
	v_mfma_f32_16x16x32_bf16 v[18:21], v[146:149], v[184:187], v[18:21]
	s_setprio 0
	s_mov_b32 m0, s93
	v_lshl_add_u64 v[50:51], v[178:179], 0, s[46:47]
	s_waitcnt vmcnt(0)
	s_barrier
	global_load_lds_dwordx4 v[50:51], off
	v_lshl_add_u64 v[50:51], v[178:179], 0, s[56:57]
	s_mov_b32 m0, s94
	s_nop 0
	global_load_lds_dwordx4 v[50:51], off
	v_lshl_add_u64 v[50:51], v[178:179], 0, s[58:59]
	s_mov_b32 m0, s95
	s_nop 0
	global_load_lds_dwordx4 v[50:51], off
	v_lshl_add_u64 v[50:51], v[178:179], 0, s[60:61]
	s_mov_b32 m0, s96
	s_nop 0
	global_load_lds_dwordx4 v[50:51], off
	v_lshl_add_u64 v[50:51], v[188:189], 0, s[62:63]
	s_mov_b32 m0, s97
	s_nop 0
	global_load_lds_dwordx4 v[50:51], off
	v_lshl_add_u64 v[50:51], v[188:189], 0, s[64:65]
	s_mov_b32 m0, s18
	s_nop 0
	global_load_lds_dwordx4 v[50:51], off
	ds_read_b128 v[50:53], v190 offset:16384
	ds_read_b128 v[138:141], v190 offset:17408
	ds_read_b128 v[142:145], v190 offset:18432
	ds_read_b128 v[146:149], v190 offset:19456
	ds_read_b128 v[150:153], v0
	ds_read_b128 v[154:157], v0 offset:1024
	ds_read_b128 v[158:161], v0 offset:2048
	ds_read_b128 v[162:165], v0 offset:3072
	ds_read_b128 v[166:169], v0 offset:4096
	ds_read_b128 v[170:173], v0 offset:5120
	ds_read_b128 v[174:177], v0 offset:6144
	ds_read_b128 v[184:187], v0 offset:7168
	s_setprio 1
	s_waitcnt lgkmcnt(0)
	v_mfma_f32_16x16x32_bf16 v[54:57], v[50:53], v[150:153], v[54:57]
	v_mfma_f32_16x16x32_bf16 v[58:61], v[138:141], v[150:153], v[58:61]
	v_mfma_f32_16x16x32_bf16 v[62:65], v[142:145], v[150:153], v[62:65]
	v_mfma_f32_16x16x32_bf16 v[22:25], v[146:149], v[150:153], v[22:25]
	v_mfma_f32_16x16x32_bf16 v[66:69], v[50:53], v[154:157], v[66:69]
	v_mfma_f32_16x16x32_bf16 v[70:73], v[138:141], v[154:157], v[70:73]
	v_mfma_f32_16x16x32_bf16 v[74:77], v[142:145], v[154:157], v[74:77]
	v_mfma_f32_16x16x32_bf16 v[26:29], v[146:149], v[154:157], v[26:29]
	v_mfma_f32_16x16x32_bf16 v[78:81], v[50:53], v[158:161], v[78:81]
	v_mfma_f32_16x16x32_bf16 v[82:85], v[138:141], v[158:161], v[82:85]
	v_mfma_f32_16x16x32_bf16 v[86:89], v[142:145], v[158:161], v[86:89]
	v_mfma_f32_16x16x32_bf16 v[30:33], v[146:149], v[158:161], v[30:33]
	v_mfma_f32_16x16x32_bf16 v[90:93], v[50:53], v[162:165], v[90:93]
	v_mfma_f32_16x16x32_bf16 v[94:97], v[138:141], v[162:165], v[94:97]
	v_mfma_f32_16x16x32_bf16 v[98:101], v[142:145], v[162:165], v[98:101]
	v_mfma_f32_16x16x32_bf16 v[34:37], v[146:149], v[162:165], v[34:37]
	v_mfma_f32_16x16x32_bf16 v[102:105], v[50:53], v[166:169], v[102:105]
	v_mfma_f32_16x16x32_bf16 v[106:109], v[138:141], v[166:169], v[106:109]
	v_mfma_f32_16x16x32_bf16 v[110:113], v[142:145], v[166:169], v[110:113]
	v_mfma_f32_16x16x32_bf16 v[38:41], v[146:149], v[166:169], v[38:41]
	v_mfma_f32_16x16x32_bf16 v[114:117], v[50:53], v[170:173], v[114:117]
	v_mfma_f32_16x16x32_bf16 v[118:121], v[138:141], v[170:173], v[118:121]
	v_mfma_f32_16x16x32_bf16 v[122:125], v[142:145], v[170:173], v[122:125]
	v_mfma_f32_16x16x32_bf16 v[42:45], v[146:149], v[170:173], v[42:45]
	v_mfma_f32_16x16x32_bf16 v[126:129], v[50:53], v[174:177], v[126:129]
	v_mfma_f32_16x16x32_bf16 v[130:133], v[138:141], v[174:177], v[130:133]
	v_mfma_f32_16x16x32_bf16 v[134:137], v[142:145], v[174:177], v[134:137]
	v_mfma_f32_16x16x32_bf16 v[46:49], v[146:149], v[174:177], v[46:49]
	v_mfma_f32_16x16x32_bf16 v[6:9], v[50:53], v[184:187], v[6:9]
	v_mfma_f32_16x16x32_bf16 v[10:13], v[138:141], v[184:187], v[10:13]
	v_mfma_f32_16x16x32_bf16 v[14:17], v[142:145], v[184:187], v[14:17]
	v_mfma_f32_16x16x32_bf16 v[18:21], v[146:149], v[184:187], v[18:21]
	s_setprio 0
	s_waitcnt vmcnt(0)
	s_barrier
	ds_read_b128 v[50:53], v190 offset:40960
	ds_read_b128 v[138:141], v190 offset:41984
	ds_read_b128 v[142:145], v190 offset:43008
	ds_read_b128 v[146:149], v190 offset:44032
	ds_read_b128 v[150:153], v0 offset:24576
	ds_read_b128 v[154:157], v0 offset:25600
	ds_read_b128 v[158:161], v0 offset:26624
	ds_read_b128 v[162:165], v0 offset:27648
	ds_read_b128 v[166:169], v0 offset:28672
	ds_read_b128 v[170:173], v0 offset:29696
	ds_read_b128 v[174:177], v0 offset:30720
	ds_read_b128 v[184:187], v0 offset:31744
	s_setprio 1
	s_waitcnt lgkmcnt(7)
	v_mfma_f32_16x16x32_bf16 v[54:57], v[50:53], v[150:153], v[54:57]
	v_mfma_f32_16x16x32_bf16 v[58:61], v[138:141], v[150:153], v[58:61]
	v_mfma_f32_16x16x32_bf16 v[62:65], v[142:145], v[150:153], v[62:65]
	v_mfma_f32_16x16x32_bf16 v[22:25], v[146:149], v[150:153], v[22:25]
	s_waitcnt lgkmcnt(6)
	v_mfma_f32_16x16x32_bf16 v[66:69], v[50:53], v[154:157], v[66:69]
	v_mfma_f32_16x16x32_bf16 v[70:73], v[138:141], v[154:157], v[70:73]
	v_mfma_f32_16x16x32_bf16 v[74:77], v[142:145], v[154:157], v[74:77]
	v_mfma_f32_16x16x32_bf16 v[26:29], v[146:149], v[154:157], v[26:29]
	s_waitcnt lgkmcnt(5)
	v_mfma_f32_16x16x32_bf16 v[78:81], v[50:53], v[158:161], v[78:81]
	v_mfma_f32_16x16x32_bf16 v[82:85], v[138:141], v[158:161], v[82:85]
	v_mfma_f32_16x16x32_bf16 v[86:89], v[142:145], v[158:161], v[86:89]
	v_mfma_f32_16x16x32_bf16 v[30:33], v[146:149], v[158:161], v[30:33]
	s_waitcnt lgkmcnt(4)
	v_mfma_f32_16x16x32_bf16 v[90:93], v[50:53], v[162:165], v[90:93]
	v_mfma_f32_16x16x32_bf16 v[94:97], v[138:141], v[162:165], v[94:97]
	v_mfma_f32_16x16x32_bf16 v[98:101], v[142:145], v[162:165], v[98:101]
	v_mfma_f32_16x16x32_bf16 v[34:37], v[146:149], v[162:165], v[34:37]
	s_waitcnt lgkmcnt(3)
	v_mfma_f32_16x16x32_bf16 v[102:105], v[50:53], v[166:169], v[102:105]
	v_mfma_f32_16x16x32_bf16 v[106:109], v[138:141], v[166:169], v[106:109]
	v_mfma_f32_16x16x32_bf16 v[110:113], v[142:145], v[166:169], v[110:113]
	v_mfma_f32_16x16x32_bf16 v[38:41], v[146:149], v[166:169], v[38:41]
	s_waitcnt lgkmcnt(2)
	v_mfma_f32_16x16x32_bf16 v[114:117], v[50:53], v[170:173], v[114:117]
	v_mfma_f32_16x16x32_bf16 v[118:121], v[138:141], v[170:173], v[118:121]
	v_mfma_f32_16x16x32_bf16 v[122:125], v[142:145], v[170:173], v[122:125]
	v_mfma_f32_16x16x32_bf16 v[42:45], v[146:149], v[170:173], v[42:45]
	s_waitcnt lgkmcnt(1)
	v_mfma_f32_16x16x32_bf16 v[126:129], v[50:53], v[174:177], v[126:129]
	v_mfma_f32_16x16x32_bf16 v[130:133], v[138:141], v[174:177], v[130:133]
	v_mfma_f32_16x16x32_bf16 v[134:137], v[142:145], v[174:177], v[134:137]
	v_mfma_f32_16x16x32_bf16 v[46:49], v[146:149], v[174:177], v[46:49]
	s_waitcnt lgkmcnt(0)
	v_mfma_f32_16x16x32_bf16 v[6:9], v[50:53], v[184:187], v[6:9]
	v_mfma_f32_16x16x32_bf16 v[10:13], v[138:141], v[184:187], v[10:13]
	v_mfma_f32_16x16x32_bf16 v[14:17], v[142:145], v[184:187], v[14:17]
	v_mfma_f32_16x16x32_bf16 v[18:21], v[146:149], v[184:187], v[18:21]
	s_setprio 0
	v_add_u32_e32 v50, s0, v4
	s_barrier
	s_ashr_i32 s79, s78, 31
	v_lshl_add_u64 v[52:53], s[78:79], 2, v[2:3]
	v_ashrrev_i32_e32 v51, 31, v50
	v_lshlrev_b64 v[138:139], 12, v[50:51]
	v_lshl_add_u64 v[138:139], v[52:53], 0, v[138:139]
	global_store_dwordx4 v[138:139], v[54:57], off
	global_store_dwordx4 v[138:139], v[58:61], off offset:64
	global_store_dwordx4 v[138:139], v[62:65], off offset:128
	global_store_dwordx4 v[138:139], v[22:25], off offset:192
	s_add_i32 s90, s90, s22
	v_ashrrev_i32_e32 v51, 31, v50
	v_lshlrev_b64 v[22:23], 12, v[50:51]
	v_lshl_add_u64 v[22:23], v[52:53], 0, v[22:23]
	v_lshl_add_u64 v[24:25], v[22:23], 0, s[66:67]
	v_add_co_u32_e32 v22, vcc, s84, v22
	s_add_i32 s80, s80, s81
	s_nop 0
	v_addc_co_u32_e32 v23, vcc, 0, v23, vcc
	global_store_dwordx4 v[22:23], v[66:69], off
	global_store_dwordx4 v[24:25], v[70:73], off offset:64
	global_store_dwordx4 v[24:25], v[74:77], off offset:128
	global_store_dwordx4 v[24:25], v[26:29], off offset:192
	s_cmp_lt_i32 s90, 64
	v_ashrrev_i32_e32 v51, 31, v50
	v_lshlrev_b64 v[22:23], 12, v[50:51]
	v_lshl_add_u64 v[22:23], v[52:53], 0, v[22:23]
	v_lshl_add_u64 v[24:25], v[22:23], 0, s[10:11]
	v_add_co_u32_e32 v22, vcc, s85, v22
	s_nop 1
	v_addc_co_u32_e32 v23, vcc, 0, v23, vcc
	global_store_dwordx4 v[22:23], v[78:81], off
	global_store_dwordx4 v[24:25], v[82:85], off offset:64
	global_store_dwordx4 v[24:25], v[86:89], off offset:128
	global_store_dwordx4 v[24:25], v[30:33], off offset:192
	s_nop 0
	v_ashrrev_i32_e32 v51, 31, v50
	v_lshlrev_b64 v[22:23], 12, v[50:51]
	v_lshl_add_u64 v[22:23], v[52:53], 0, v[22:23]
	v_lshl_add_u64 v[24:25], v[22:23], 0, s[68:69]
	v_add_co_u32_e32 v22, vcc, s86, v22
	s_nop 1
	v_addc_co_u32_e32 v23, vcc, 0, v23, vcc
	global_store_dwordx4 v[22:23], v[90:93], off
	global_store_dwordx4 v[24:25], v[94:97], off offset:64
	global_store_dwordx4 v[24:25], v[98:101], off offset:128
	global_store_dwordx4 v[24:25], v[34:37], off offset:192
	s_nop 0
	v_ashrrev_i32_e32 v51, 31, v50
	v_lshlrev_b64 v[22:23], 12, v[50:51]
	v_lshl_add_u64 v[22:23], v[52:53], 0, v[22:23]
	v_lshl_add_u64 v[24:25], v[22:23], 0, s[70:71]
	v_add_co_u32_e32 v22, vcc, s87, v22
	s_nop 1
	v_addc_co_u32_e32 v23, vcc, 0, v23, vcc
	global_store_dwordx4 v[22:23], v[102:105], off
	global_store_dwordx4 v[24:25], v[106:109], off offset:64
	global_store_dwordx4 v[24:25], v[110:113], off offset:128
	global_store_dwordx4 v[24:25], v[38:41], off offset:192
	s_nop 0
	v_ashrrev_i32_e32 v51, 31, v50
	v_lshlrev_b64 v[22:23], 12, v[50:51]
	v_lshl_add_u64 v[22:23], v[52:53], 0, v[22:23]
	v_lshl_add_u64 v[24:25], v[22:23], 0, s[72:73]
	v_add_co_u32_e32 v22, vcc, s88, v22
	s_nop 1
	v_addc_co_u32_e32 v23, vcc, 0, v23, vcc
	global_store_dwordx4 v[22:23], v[114:117], off
	global_store_dwordx4 v[24:25], v[118:121], off offset:64
	global_store_dwordx4 v[24:25], v[122:125], off offset:128
	global_store_dwordx4 v[24:25], v[42:45], off offset:192
	s_nop 0
	v_ashrrev_i32_e32 v51, 31, v50
	v_lshlrev_b64 v[22:23], 12, v[50:51]
	v_lshl_add_u64 v[22:23], v[52:53], 0, v[22:23]
	v_lshl_add_u64 v[24:25], v[22:23], 0, s[74:75]
	v_add_co_u32_e32 v22, vcc, s89, v22
	s_nop 1
	v_addc_co_u32_e32 v23, vcc, 0, v23, vcc
	global_store_dwordx4 v[22:23], v[126:129], off
	global_store_dwordx4 v[24:25], v[130:133], off offset:64
	global_store_dwordx4 v[24:25], v[134:137], off offset:128
	global_store_dwordx4 v[24:25], v[46:49], off offset:192
	s_nop 0
	v_ashrrev_i32_e32 v51, 31, v50
	v_lshlrev_b64 v[22:23], 12, v[50:51]
	v_lshl_add_u64 v[22:23], v[52:53], 0, v[22:23]
	v_lshl_add_u64 v[24:25], v[22:23], 0, s[76:77]
	v_add_co_u32_e32 v22, vcc, 0x70000, v22
	s_nop 1
	v_addc_co_u32_e32 v23, vcc, 0, v23, vcc
	global_store_dwordx4 v[22:23], v[6:9], off
	global_store_dwordx4 v[24:25], v[10:13], off offset:64
	global_store_dwordx4 v[24:25], v[14:17], off offset:128
	global_store_dwordx4 v[24:25], v[18:21], off offset:192
	s_cbranch_scc1 .LBB0_1166
	v_readlane_b32 s94, v244, 4
	v_readlane_b32 s95, v244, 5
